# GEMM K-loop heads aligned to 8 bytes (.p2align 3 before each of the 22 loop labels)
# baseline (speedup 1.0000x reference)
.LBB0_162:
	s_ashr_i32 s19, s18, 31
	s_lshl_b64 s[20:21], s[18:19], 19
	s_add_u32 s20, s8, s20
	s_addc_u32 s21, s9, s21
	s_and_b64 s[22:23], s[4:5], exec
	s_cselect_b32 s19, s21, s27
	s_cselect_b32 s51, s20, s26
	s_ashr_i32 s17, s16, 31
	s_lshl_b64 s[22:23], s[16:17], 19
	s_add_u32 s22, s31, s22
	s_addc_u32 s23, s34, s23
	s_and_b64 s[28:29], s[4:5], exec
	s_cselect_b32 s17, s23, s25
	s_cselect_b32 s52, s22, s24
	s_add_u32 s53, s24, 0x100
	s_addc_u32 s54, s25, 0
	s_add_u32 s24, s26, 0x40080
	v_mov_b32_e32 v0, 0
	s_addc_u32 s25, s27, 0
	s_mov_b32 s55, -2
	v_mov_b32_e32 v1, v0
	v_mov_b32_e32 v2, v0
	v_mov_b32_e32 v3, v0
	v_mov_b32_e32 v4, v0
	v_mov_b32_e32 v5, v0
	v_mov_b32_e32 v6, v0
	v_mov_b32_e32 v7, v0
	v_mov_b32_e32 v16, v0
	v_mov_b32_e32 v17, v0
	s_waitcnt vmcnt(0)
	v_mov_b32_e32 v18, v0
	v_mov_b32_e32 v19, v0
	v_mov_b32_e32 v20, v0
	v_mov_b32_e32 v21, v0
	v_mov_b32_e32 v22, v0
	v_mov_b32_e32 v23, v0
	v_mov_b32_e32 v32, v0
	v_mov_b32_e32 v33, v0
	v_mov_b32_e32 v34, v0
	v_mov_b32_e32 v35, v0
	v_mov_b32_e32 v36, v0
	v_mov_b32_e32 v37, v0
	v_mov_b32_e32 v38, v0
	v_mov_b32_e32 v39, v0
	v_mov_b32_e32 v48, v0
	v_mov_b32_e32 v49, v0
	v_mov_b32_e32 v50, v0
	v_mov_b32_e32 v51, v0
	v_mov_b32_e32 v52, v0
	v_mov_b32_e32 v53, v0
	v_mov_b32_e32 v54, v0
	v_mov_b32_e32 v55, v0
	v_mov_b32_e32 v8, v0
	v_mov_b32_e32 v9, v0
	v_mov_b32_e32 v10, v0
	v_mov_b32_e32 v11, v0
	v_mov_b32_e32 v12, v0
	v_mov_b32_e32 v13, v0
	v_mov_b32_e32 v14, v0
	v_mov_b32_e32 v15, v0
	v_mov_b32_e32 v24, v0
	v_mov_b32_e32 v25, v0
	v_mov_b32_e32 v26, v0
	v_mov_b32_e32 v27, v0
	v_mov_b32_e32 v28, v0
	v_mov_b32_e32 v29, v0
	v_mov_b32_e32 v30, v0
	v_mov_b32_e32 v31, v0
	v_mov_b32_e32 v40, v0
	v_mov_b32_e32 v41, v0
	v_mov_b32_e32 v42, v0
	v_mov_b32_e32 v43, v0
	v_mov_b32_e32 v44, v0
	v_mov_b32_e32 v45, v0
	v_mov_b32_e32 v46, v0
	v_mov_b32_e32 v47, v0
	v_mov_b32_e32 v56, v0
	v_mov_b32_e32 v57, v0
	v_mov_b32_e32 v58, v0
	v_mov_b32_e32 v59, v0
	v_mov_b32_e32 v60, v0
	v_mov_b32_e32 v61, v0
	v_mov_b32_e32 v62, v0
	v_mov_b32_e32 v63, v0
	v_mov_b32_e32 v64, v0
	v_mov_b32_e32 v65, v0
	v_mov_b32_e32 v66, v0
	v_mov_b32_e32 v67, v0
	v_mov_b32_e32 v68, v0
	v_mov_b32_e32 v69, v0
	v_mov_b32_e32 v70, v0
	v_mov_b32_e32 v71, v0
	v_mov_b32_e32 v80, v0
	v_mov_b32_e32 v81, v0
	v_mov_b32_e32 v82, v0
	v_mov_b32_e32 v83, v0
	v_mov_b32_e32 v84, v0
	v_mov_b32_e32 v85, v0
	v_mov_b32_e32 v86, v0
	v_mov_b32_e32 v87, v0
	v_mov_b32_e32 v96, v0
	v_mov_b32_e32 v97, v0
	v_mov_b32_e32 v98, v0
	v_mov_b32_e32 v99, v0
	v_mov_b32_e32 v100, v0
	v_mov_b32_e32 v101, v0
	v_mov_b32_e32 v102, v0
	v_mov_b32_e32 v103, v0
	v_mov_b32_e32 v112, v0
	v_mov_b32_e32 v113, v0
	v_mov_b32_e32 v114, v0
	v_mov_b32_e32 v115, v0
	v_mov_b32_e32 v116, v0
	v_mov_b32_e32 v117, v0
	v_mov_b32_e32 v118, v0
	v_mov_b32_e32 v119, v0
	v_mov_b32_e32 v72, v0
	v_mov_b32_e32 v73, v0
	v_mov_b32_e32 v74, v0
	v_mov_b32_e32 v75, v0
	v_mov_b32_e32 v76, v0
	v_mov_b32_e32 v77, v0
	v_mov_b32_e32 v78, v0
	v_mov_b32_e32 v79, v0
	v_mov_b32_e32 v88, v0
	v_mov_b32_e32 v89, v0
	v_mov_b32_e32 v90, v0
	v_mov_b32_e32 v91, v0
	v_mov_b32_e32 v92, v0
	v_mov_b32_e32 v93, v0
	v_mov_b32_e32 v94, v0
	v_mov_b32_e32 v95, v0
	v_mov_b32_e32 v104, v0
	v_mov_b32_e32 v105, v0
	v_mov_b32_e32 v106, v0
	v_mov_b32_e32 v107, v0
	v_mov_b32_e32 v108, v0
	v_mov_b32_e32 v109, v0
	v_mov_b32_e32 v110, v0
	v_mov_b32_e32 v111, v0
	v_mov_b32_e32 v120, v0
	v_mov_b32_e32 v121, v0
	v_mov_b32_e32 v122, v0
	v_mov_b32_e32 v123, v0
	v_mov_b32_e32 v124, v0
	v_mov_b32_e32 v125, v0
	v_mov_b32_e32 v126, v0
	v_mov_b32_e32 v127, v0
	v_add_u32_e32 v204, 0x80, v128
	v_add_u32_e32 v205, 0x80, v130
	v_add_u32_e32 v220, 0x80, v132
	v_add_u32_e32 v221, 0x80, v134
	.p2align	3

.LBB0_605:
	s_ashr_i32 s21, s20, 31
	s_lshl_b64 s[22:23], s[20:21], 19
	s_add_u32 s22, s39, s22
	s_addc_u32 s23, s40, s23
	s_and_b64 s[24:25], s[6:7], exec
	s_cselect_b32 s21, s23, s29
	s_cselect_b32 s27, s22, s28
	s_ashr_i32 s19, s18, 31
	s_lshl_b64 s[24:25], s[18:19], 19
	s_add_u32 s24, s41, s24
	s_addc_u32 s25, s42, s25
	s_and_b64 s[34:35], s[6:7], exec
	s_cselect_b32 s19, s25, s31
	s_cselect_b32 s55, s24, s30
	s_add_u32 s56, s30, 0x100
	v_mov_b32_e32 v0, 0
	s_addc_u32 s57, s31, 0
	s_mov_b32 s58, -2
	v_mov_b32_e32 v1, v0
	v_mov_b32_e32 v2, v0
	v_mov_b32_e32 v3, v0
	v_mov_b32_e32 v4, v0
	v_mov_b32_e32 v5, v0
	v_mov_b32_e32 v6, v0
	v_mov_b32_e32 v7, v0
	v_mov_b32_e32 v16, v0
	v_mov_b32_e32 v17, v0
	v_mov_b32_e32 v18, v0
	v_mov_b32_e32 v19, v0
	v_mov_b32_e32 v20, v0
	v_mov_b32_e32 v21, v0
	v_mov_b32_e32 v22, v0
	v_mov_b32_e32 v23, v0
	v_mov_b32_e32 v32, v0
	v_mov_b32_e32 v33, v0
	v_mov_b32_e32 v34, v0
	v_mov_b32_e32 v35, v0
	v_mov_b32_e32 v36, v0
	v_mov_b32_e32 v37, v0
	v_mov_b32_e32 v38, v0
	v_mov_b32_e32 v39, v0
	v_mov_b32_e32 v48, v0
	v_mov_b32_e32 v49, v0
	v_mov_b32_e32 v50, v0
	v_mov_b32_e32 v51, v0
	v_mov_b32_e32 v52, v0
	v_mov_b32_e32 v53, v0
	v_mov_b32_e32 v54, v0
	v_mov_b32_e32 v55, v0
	v_mov_b32_e32 v8, v0
	v_mov_b32_e32 v9, v0
	v_mov_b32_e32 v10, v0
	v_mov_b32_e32 v11, v0
	v_mov_b32_e32 v12, v0
	v_mov_b32_e32 v13, v0
	v_mov_b32_e32 v14, v0
	v_mov_b32_e32 v15, v0
	v_mov_b32_e32 v24, v0
	v_mov_b32_e32 v25, v0
	v_mov_b32_e32 v26, v0
	v_mov_b32_e32 v27, v0
	v_mov_b32_e32 v28, v0
	v_mov_b32_e32 v29, v0
	v_mov_b32_e32 v30, v0
	v_mov_b32_e32 v31, v0
	v_mov_b32_e32 v40, v0
	v_mov_b32_e32 v41, v0
	v_mov_b32_e32 v42, v0
	v_mov_b32_e32 v43, v0
	v_mov_b32_e32 v44, v0
	v_mov_b32_e32 v45, v0
	v_mov_b32_e32 v46, v0
	v_mov_b32_e32 v47, v0
	v_mov_b32_e32 v56, v0
	v_mov_b32_e32 v57, v0
	v_mov_b32_e32 v58, v0
	v_mov_b32_e32 v59, v0
	v_mov_b32_e32 v60, v0
	v_mov_b32_e32 v61, v0
	v_mov_b32_e32 v62, v0
	v_mov_b32_e32 v63, v0
	v_mov_b32_e32 v64, v0
	v_mov_b32_e32 v65, v0
	v_mov_b32_e32 v66, v0
	v_mov_b32_e32 v67, v0
	v_mov_b32_e32 v68, v0
	v_mov_b32_e32 v69, v0
	v_mov_b32_e32 v70, v0
	v_mov_b32_e32 v71, v0
	v_mov_b32_e32 v80, v0
	v_mov_b32_e32 v81, v0
	v_mov_b32_e32 v82, v0
	v_mov_b32_e32 v83, v0
	v_mov_b32_e32 v84, v0
	v_mov_b32_e32 v85, v0
	v_mov_b32_e32 v86, v0
	v_mov_b32_e32 v87, v0
	v_mov_b32_e32 v96, v0
	v_mov_b32_e32 v97, v0
	v_mov_b32_e32 v98, v0
	v_mov_b32_e32 v99, v0
	v_mov_b32_e32 v100, v0
	v_mov_b32_e32 v101, v0
	v_mov_b32_e32 v102, v0
	v_mov_b32_e32 v103, v0
	v_mov_b32_e32 v112, v0
	v_mov_b32_e32 v113, v0
	v_mov_b32_e32 v114, v0
	v_mov_b32_e32 v115, v0
	v_mov_b32_e32 v116, v0
	v_mov_b32_e32 v117, v0
	v_mov_b32_e32 v118, v0
	v_mov_b32_e32 v119, v0
	v_mov_b32_e32 v72, v0
	v_mov_b32_e32 v73, v0
	v_mov_b32_e32 v74, v0
	v_mov_b32_e32 v75, v0
	v_mov_b32_e32 v76, v0
	v_mov_b32_e32 v77, v0
	v_mov_b32_e32 v78, v0
	v_mov_b32_e32 v79, v0
	v_mov_b32_e32 v88, v0
	v_mov_b32_e32 v89, v0
	v_mov_b32_e32 v90, v0
	v_mov_b32_e32 v91, v0
	v_mov_b32_e32 v92, v0
	v_mov_b32_e32 v93, v0
	v_mov_b32_e32 v94, v0
	v_mov_b32_e32 v95, v0
	v_mov_b32_e32 v104, v0
	v_mov_b32_e32 v105, v0
	v_mov_b32_e32 v106, v0
	v_mov_b32_e32 v107, v0
	v_mov_b32_e32 v108, v0
	v_mov_b32_e32 v109, v0
	v_mov_b32_e32 v110, v0
	v_mov_b32_e32 v111, v0
	v_mov_b32_e32 v120, v0
	v_mov_b32_e32 v121, v0
	v_mov_b32_e32 v122, v0
	v_mov_b32_e32 v123, v0
	v_mov_b32_e32 v124, v0
	v_mov_b32_e32 v125, v0
	v_mov_b32_e32 v126, v0
	v_mov_b32_e32 v127, v0
	v_add_u32_e32 v212, 0x80, v128
	v_add_u32_e32 v213, 0x80, v130
	.p2align	3

.LBB0_698:
	s_ashr_i32 s21, s20, 31
	s_lshl_b64 s[22:23], s[20:21], 19
	s_add_u32 s22, s8, s22
	s_addc_u32 s23, s9, s23
	s_and_b64 s[24:25], s[4:5], exec
	s_cselect_b32 s21, s23, s29
	s_cselect_b32 s49, s22, s28
	s_ashr_i32 s19, s18, 31
	s_lshl_b64 s[24:25], s[18:19], 19
	s_add_u32 s24, s36, s24
	s_addc_u32 s25, s37, s25
	s_and_b64 s[30:31], s[4:5], exec
	s_cselect_b32 s19, s25, s27
	s_cselect_b32 s50, s24, s26
	s_add_u32 s51, s26, 0x100
	s_addc_u32 s52, s27, 0
	s_add_u32 s26, s28, 0x40080
	v_mov_b32_e32 v0, 0
	s_addc_u32 s27, s29, 0
	s_mov_b32 s53, -2
	v_mov_b32_e32 v1, v0
	v_mov_b32_e32 v2, v0
	v_mov_b32_e32 v3, v0
	v_mov_b32_e32 v4, v0
	v_mov_b32_e32 v5, v0
	v_mov_b32_e32 v6, v0
	v_mov_b32_e32 v7, v0
	v_mov_b32_e32 v16, v0
	v_mov_b32_e32 v17, v0
	v_mov_b32_e32 v18, v0
	v_mov_b32_e32 v19, v0
	v_mov_b32_e32 v20, v0
	v_mov_b32_e32 v21, v0
	v_mov_b32_e32 v22, v0
	v_mov_b32_e32 v23, v0
	v_mov_b32_e32 v32, v0
	v_mov_b32_e32 v33, v0
	v_mov_b32_e32 v34, v0
	v_mov_b32_e32 v35, v0
	v_mov_b32_e32 v36, v0
	v_mov_b32_e32 v37, v0
	v_mov_b32_e32 v38, v0
	v_mov_b32_e32 v39, v0
	v_mov_b32_e32 v48, v0
	v_mov_b32_e32 v49, v0
	v_mov_b32_e32 v50, v0
	v_mov_b32_e32 v51, v0
	v_mov_b32_e32 v52, v0
	v_mov_b32_e32 v53, v0
	v_mov_b32_e32 v54, v0
	v_mov_b32_e32 v55, v0
	v_mov_b32_e32 v8, v0
	v_mov_b32_e32 v9, v0
	v_mov_b32_e32 v10, v0
	v_mov_b32_e32 v11, v0
	v_mov_b32_e32 v12, v0
	v_mov_b32_e32 v13, v0
	v_mov_b32_e32 v14, v0
	v_mov_b32_e32 v15, v0
	v_mov_b32_e32 v24, v0
	v_mov_b32_e32 v25, v0
	v_mov_b32_e32 v26, v0
	v_mov_b32_e32 v27, v0
	v_mov_b32_e32 v28, v0
	v_mov_b32_e32 v29, v0
	v_mov_b32_e32 v30, v0
	v_mov_b32_e32 v31, v0
	v_mov_b32_e32 v40, v0
	v_mov_b32_e32 v41, v0
	v_mov_b32_e32 v42, v0
	v_mov_b32_e32 v43, v0
	v_mov_b32_e32 v44, v0
	v_mov_b32_e32 v45, v0
	v_mov_b32_e32 v46, v0
	v_mov_b32_e32 v47, v0
	v_mov_b32_e32 v56, v0
	v_mov_b32_e32 v57, v0
	v_mov_b32_e32 v58, v0
	v_mov_b32_e32 v59, v0
	v_mov_b32_e32 v60, v0
	v_mov_b32_e32 v61, v0
	v_mov_b32_e32 v62, v0
	v_mov_b32_e32 v63, v0
	v_mov_b32_e32 v64, v0
	v_mov_b32_e32 v65, v0
	v_mov_b32_e32 v66, v0
	v_mov_b32_e32 v67, v0
	v_mov_b32_e32 v68, v0
	v_mov_b32_e32 v69, v0
	v_mov_b32_e32 v70, v0
	v_mov_b32_e32 v71, v0
	v_mov_b32_e32 v80, v0
	v_mov_b32_e32 v81, v0
	v_mov_b32_e32 v82, v0
	v_mov_b32_e32 v83, v0
	v_mov_b32_e32 v84, v0
	v_mov_b32_e32 v85, v0
	v_mov_b32_e32 v86, v0
	v_mov_b32_e32 v87, v0
	v_mov_b32_e32 v96, v0
	v_mov_b32_e32 v97, v0
	v_mov_b32_e32 v98, v0
	v_mov_b32_e32 v99, v0
	v_mov_b32_e32 v100, v0
	v_mov_b32_e32 v101, v0
	v_mov_b32_e32 v102, v0
	v_mov_b32_e32 v103, v0
	v_mov_b32_e32 v112, v0
	v_mov_b32_e32 v113, v0
	v_mov_b32_e32 v114, v0
	v_mov_b32_e32 v115, v0
	v_mov_b32_e32 v116, v0
	v_mov_b32_e32 v117, v0
	v_mov_b32_e32 v118, v0
	v_mov_b32_e32 v119, v0
	v_mov_b32_e32 v72, v0
	v_mov_b32_e32 v73, v0
	v_mov_b32_e32 v74, v0
	v_mov_b32_e32 v75, v0
	v_mov_b32_e32 v76, v0
	v_mov_b32_e32 v77, v0
	v_mov_b32_e32 v78, v0
	v_mov_b32_e32 v79, v0
	v_mov_b32_e32 v88, v0
	v_mov_b32_e32 v89, v0
	v_mov_b32_e32 v90, v0
	v_mov_b32_e32 v91, v0
	v_mov_b32_e32 v92, v0
	v_mov_b32_e32 v93, v0
	v_mov_b32_e32 v94, v0
	v_mov_b32_e32 v95, v0
	v_mov_b32_e32 v104, v0
	v_mov_b32_e32 v105, v0
	v_mov_b32_e32 v106, v0
	v_mov_b32_e32 v107, v0
	v_mov_b32_e32 v108, v0
	v_mov_b32_e32 v109, v0
	v_mov_b32_e32 v110, v0
	v_mov_b32_e32 v111, v0
	v_mov_b32_e32 v120, v0
	v_mov_b32_e32 v121, v0
	v_mov_b32_e32 v122, v0
	v_mov_b32_e32 v123, v0
	v_mov_b32_e32 v124, v0
	v_mov_b32_e32 v125, v0
	v_mov_b32_e32 v126, v0
	v_mov_b32_e32 v127, v0
	v_add_u32_e32 v204, 0x80, v128
	v_add_u32_e32 v205, 0x80, v130
	v_add_u32_e32 v220, 0x80, v132
	v_add_u32_e32 v221, 0x80, v134
	.p2align	3

.LBB0_777:
	s_ashr_i32 s21, s20, 31
	s_lshl_b64 s[22:23], s[20:21], 21
	s_add_u32 s22, s39, s22
	s_addc_u32 s23, s40, s23
	s_and_b64 s[24:25], s[6:7], exec
	s_cselect_b32 s21, s23, s29
	s_cselect_b32 s27, s22, s28
	s_ashr_i32 s19, s18, 31
	s_lshl_b64 s[24:25], s[18:19], 21
	s_add_u32 s24, s41, s24
	s_addc_u32 s25, s42, s25
	s_and_b64 s[34:35], s[6:7], exec
	s_cselect_b32 s19, s25, s31
	s_cselect_b32 s55, s24, s30
	s_add_u32 s56, s30, 0x100
	v_mov_b32_e32 v0, 0
	s_addc_u32 s57, s31, 0
	s_mov_b32 s58, -2
	v_mov_b32_e32 v1, v0
	v_mov_b32_e32 v2, v0
	v_mov_b32_e32 v3, v0
	v_mov_b32_e32 v4, v0
	v_mov_b32_e32 v5, v0
	v_mov_b32_e32 v6, v0
	v_mov_b32_e32 v7, v0
	v_mov_b32_e32 v16, v0
	v_mov_b32_e32 v17, v0
	v_mov_b32_e32 v18, v0
	v_mov_b32_e32 v19, v0
	v_mov_b32_e32 v20, v0
	v_mov_b32_e32 v21, v0
	v_mov_b32_e32 v22, v0
	v_mov_b32_e32 v23, v0
	v_mov_b32_e32 v32, v0
	v_mov_b32_e32 v33, v0
	v_mov_b32_e32 v34, v0
	v_mov_b32_e32 v35, v0
	v_mov_b32_e32 v36, v0
	v_mov_b32_e32 v37, v0
	v_mov_b32_e32 v38, v0
	v_mov_b32_e32 v39, v0
	v_mov_b32_e32 v48, v0
	v_mov_b32_e32 v49, v0
	v_mov_b32_e32 v50, v0
	v_mov_b32_e32 v51, v0
	v_mov_b32_e32 v52, v0
	v_mov_b32_e32 v53, v0
	v_mov_b32_e32 v54, v0
	v_mov_b32_e32 v55, v0
	v_mov_b32_e32 v8, v0
	v_mov_b32_e32 v9, v0
	v_mov_b32_e32 v10, v0
	v_mov_b32_e32 v11, v0
	v_mov_b32_e32 v12, v0
	v_mov_b32_e32 v13, v0
	v_mov_b32_e32 v14, v0
	v_mov_b32_e32 v15, v0
	v_mov_b32_e32 v24, v0
	v_mov_b32_e32 v25, v0
	v_mov_b32_e32 v26, v0
	v_mov_b32_e32 v27, v0
	v_mov_b32_e32 v28, v0
	v_mov_b32_e32 v29, v0
	v_mov_b32_e32 v30, v0
	v_mov_b32_e32 v31, v0
	v_mov_b32_e32 v40, v0
	v_mov_b32_e32 v41, v0
	v_mov_b32_e32 v42, v0
	v_mov_b32_e32 v43, v0
	v_mov_b32_e32 v44, v0
	v_mov_b32_e32 v45, v0
	v_mov_b32_e32 v46, v0
	v_mov_b32_e32 v47, v0
	v_mov_b32_e32 v56, v0
	v_mov_b32_e32 v57, v0
	v_mov_b32_e32 v58, v0
	v_mov_b32_e32 v59, v0
	v_mov_b32_e32 v60, v0
	v_mov_b32_e32 v61, v0
	v_mov_b32_e32 v62, v0
	v_mov_b32_e32 v63, v0
	v_mov_b32_e32 v64, v0
	v_mov_b32_e32 v65, v0
	v_mov_b32_e32 v66, v0
	v_mov_b32_e32 v67, v0
	v_mov_b32_e32 v68, v0
	v_mov_b32_e32 v69, v0
	v_mov_b32_e32 v70, v0
	v_mov_b32_e32 v71, v0
	v_mov_b32_e32 v80, v0
	v_mov_b32_e32 v81, v0
	v_mov_b32_e32 v82, v0
	v_mov_b32_e32 v83, v0
	v_mov_b32_e32 v84, v0
	v_mov_b32_e32 v85, v0
	v_mov_b32_e32 v86, v0
	v_mov_b32_e32 v87, v0
	v_mov_b32_e32 v96, v0
	v_mov_b32_e32 v97, v0
	v_mov_b32_e32 v98, v0
	v_mov_b32_e32 v99, v0
	v_mov_b32_e32 v100, v0
	v_mov_b32_e32 v101, v0
	v_mov_b32_e32 v102, v0
	v_mov_b32_e32 v103, v0
	v_mov_b32_e32 v112, v0
	v_mov_b32_e32 v113, v0
	v_mov_b32_e32 v114, v0
	v_mov_b32_e32 v115, v0
	v_mov_b32_e32 v116, v0
	v_mov_b32_e32 v117, v0
	v_mov_b32_e32 v118, v0
	v_mov_b32_e32 v119, v0
	v_mov_b32_e32 v72, v0
	v_mov_b32_e32 v73, v0
	v_mov_b32_e32 v74, v0
	v_mov_b32_e32 v75, v0
	v_mov_b32_e32 v76, v0
	v_mov_b32_e32 v77, v0
	v_mov_b32_e32 v78, v0
	v_mov_b32_e32 v79, v0
	v_mov_b32_e32 v88, v0
	v_mov_b32_e32 v89, v0
	v_mov_b32_e32 v90, v0
	v_mov_b32_e32 v91, v0
	v_mov_b32_e32 v92, v0
	v_mov_b32_e32 v93, v0
	v_mov_b32_e32 v94, v0
	v_mov_b32_e32 v95, v0
	v_mov_b32_e32 v104, v0
	v_mov_b32_e32 v105, v0
	v_mov_b32_e32 v106, v0
	v_mov_b32_e32 v107, v0
	v_mov_b32_e32 v108, v0
	v_mov_b32_e32 v109, v0
	v_mov_b32_e32 v110, v0
	v_mov_b32_e32 v111, v0
	v_mov_b32_e32 v120, v0
	v_mov_b32_e32 v121, v0
	v_mov_b32_e32 v122, v0
	v_mov_b32_e32 v123, v0
	v_mov_b32_e32 v124, v0
	v_mov_b32_e32 v125, v0
	v_mov_b32_e32 v126, v0
	v_mov_b32_e32 v127, v0
	v_add_u32_e32 v212, 0x80, v128
	v_add_u32_e32 v213, 0x80, v130
	.p2align	3

.LBB0_894:
	s_ashr_i32 s29, s28, 31
	s_lshl_b64 s[30:31], s[28:29], 19
	s_add_u32 s30, s8, s30
	s_addc_u32 s31, s9, s31
	s_and_b64 s[34:35], s[6:7], exec
	s_cselect_b32 s3, s31, s39
	s_cselect_b32 s29, s30, s38
	s_ashr_i32 s27, s26, 31
	s_lshl_b64 s[34:35], s[26:27], 19
	s_add_u32 s34, s43, s34
	s_addc_u32 s35, s44, s35
	s_and_b64 s[40:41], s[6:7], exec
	s_cselect_b32 s27, s35, s37
	s_cselect_b32 s58, s34, s36
	s_add_u32 s59, s36, 0x100
	s_addc_u32 s60, s37, 0
	s_add_u32 s36, s38, 0x40080
	v_mov_b32_e32 v0, 0
	s_addc_u32 s37, s39, 0
	s_mov_b32 s61, -2
	v_mov_b32_e32 v1, v0
	v_mov_b32_e32 v2, v0
	v_mov_b32_e32 v3, v0
	v_mov_b32_e32 v4, v0
	v_mov_b32_e32 v5, v0
	v_mov_b32_e32 v6, v0
	v_mov_b32_e32 v7, v0
	v_mov_b32_e32 v16, v0
	v_mov_b32_e32 v17, v0
	v_mov_b32_e32 v18, v0
	v_mov_b32_e32 v19, v0
	v_mov_b32_e32 v20, v0
	v_mov_b32_e32 v21, v0
	v_mov_b32_e32 v22, v0
	v_mov_b32_e32 v23, v0
	v_mov_b32_e32 v32, v0
	v_mov_b32_e32 v33, v0
	v_mov_b32_e32 v34, v0
	v_mov_b32_e32 v35, v0
	v_mov_b32_e32 v36, v0
	v_mov_b32_e32 v37, v0
	v_mov_b32_e32 v38, v0
	v_mov_b32_e32 v39, v0
	v_mov_b32_e32 v48, v0
	v_mov_b32_e32 v49, v0
	v_mov_b32_e32 v50, v0
	v_mov_b32_e32 v51, v0
	v_mov_b32_e32 v52, v0
	v_mov_b32_e32 v53, v0
	v_mov_b32_e32 v54, v0
	v_mov_b32_e32 v55, v0
	v_mov_b32_e32 v8, v0
	v_mov_b32_e32 v9, v0
	v_mov_b32_e32 v10, v0
	v_mov_b32_e32 v11, v0
	v_mov_b32_e32 v12, v0
	v_mov_b32_e32 v13, v0
	v_mov_b32_e32 v14, v0
	v_mov_b32_e32 v15, v0
	v_mov_b32_e32 v24, v0
	v_mov_b32_e32 v25, v0
	v_mov_b32_e32 v26, v0
	v_mov_b32_e32 v27, v0
	v_mov_b32_e32 v28, v0
	v_mov_b32_e32 v29, v0
	v_mov_b32_e32 v30, v0
	v_mov_b32_e32 v31, v0
	v_mov_b32_e32 v40, v0
	v_mov_b32_e32 v41, v0
	v_mov_b32_e32 v42, v0
	v_mov_b32_e32 v43, v0
	v_mov_b32_e32 v44, v0
	v_mov_b32_e32 v45, v0
	v_mov_b32_e32 v46, v0
	v_mov_b32_e32 v47, v0
	v_mov_b32_e32 v56, v0
	v_mov_b32_e32 v57, v0
	v_mov_b32_e32 v58, v0
	v_mov_b32_e32 v59, v0
	v_mov_b32_e32 v60, v0
	v_mov_b32_e32 v61, v0
	v_mov_b32_e32 v62, v0
	v_mov_b32_e32 v63, v0
	v_mov_b32_e32 v64, v0
	v_mov_b32_e32 v65, v0
	v_mov_b32_e32 v66, v0
	v_mov_b32_e32 v67, v0
	v_mov_b32_e32 v68, v0
	v_mov_b32_e32 v69, v0
	v_mov_b32_e32 v70, v0
	v_mov_b32_e32 v71, v0
	v_mov_b32_e32 v80, v0
	v_mov_b32_e32 v81, v0
	v_mov_b32_e32 v82, v0
	v_mov_b32_e32 v83, v0
	v_mov_b32_e32 v84, v0
	v_mov_b32_e32 v85, v0
	v_mov_b32_e32 v86, v0
	v_mov_b32_e32 v87, v0
	v_mov_b32_e32 v96, v0
	v_mov_b32_e32 v97, v0
	v_mov_b32_e32 v98, v0
	v_mov_b32_e32 v99, v0
	v_mov_b32_e32 v100, v0
	v_mov_b32_e32 v101, v0
	v_mov_b32_e32 v102, v0
	v_mov_b32_e32 v103, v0
	v_mov_b32_e32 v112, v0
	v_mov_b32_e32 v113, v0
	v_mov_b32_e32 v114, v0
	v_mov_b32_e32 v115, v0
	v_mov_b32_e32 v116, v0
	v_mov_b32_e32 v117, v0
	v_mov_b32_e32 v118, v0
	v_mov_b32_e32 v119, v0
	v_mov_b32_e32 v72, v0
	v_mov_b32_e32 v73, v0
	v_mov_b32_e32 v74, v0
	v_mov_b32_e32 v75, v0
	v_mov_b32_e32 v76, v0
	v_mov_b32_e32 v77, v0
	v_mov_b32_e32 v78, v0
	v_mov_b32_e32 v79, v0
	v_mov_b32_e32 v88, v0
	v_mov_b32_e32 v89, v0
	v_mov_b32_e32 v90, v0
	v_mov_b32_e32 v91, v0
	v_mov_b32_e32 v92, v0
	v_mov_b32_e32 v93, v0
	v_mov_b32_e32 v94, v0
	v_mov_b32_e32 v95, v0
	v_mov_b32_e32 v104, v0
	v_mov_b32_e32 v105, v0
	v_mov_b32_e32 v106, v0
	v_mov_b32_e32 v107, v0
	v_mov_b32_e32 v108, v0
	v_mov_b32_e32 v109, v0
	v_mov_b32_e32 v110, v0
	v_mov_b32_e32 v111, v0
	v_mov_b32_e32 v120, v0
	v_mov_b32_e32 v121, v0
	v_mov_b32_e32 v122, v0
	v_mov_b32_e32 v123, v0
	v_mov_b32_e32 v124, v0
	v_mov_b32_e32 v125, v0
	v_mov_b32_e32 v126, v0
	v_mov_b32_e32 v127, v0
	v_add_u32_e32 v148, 0x80, v128
	v_add_u32_e32 v149, 0x80, v130
	.p2align	3

.LBB0_987:
	s_ashr_i32 s19, s18, 31
	s_lshl_b64 s[6:7], s[18:19], 19
	s_add_u32 s20, s34, s6
	s_addc_u32 s21, s35, s7
	s_and_b64 s[6:7], s[4:5], exec
	s_cselect_b32 s19, s21, s29
	s_cselect_b32 s49, s20, s28
	s_ashr_i32 s17, s16, 31
	s_lshl_b64 s[6:7], s[16:17], 19
	s_add_u32 s22, s36, s6
	s_addc_u32 s23, s37, s7
	s_and_b64 s[6:7], s[4:5], exec
	s_cselect_b32 s17, s23, s27
	s_cselect_b32 s50, s22, s26
	s_add_u32 s51, s26, 0x100
	s_addc_u32 s52, s27, 0
	s_add_u32 s6, s28, 0x40080
	v_mov_b32_e32 v0, 0
	s_addc_u32 s7, s29, 0
	s_mov_b32 s53, -2
	v_mov_b32_e32 v1, v0
	v_mov_b32_e32 v2, v0
	v_mov_b32_e32 v3, v0
	v_mov_b32_e32 v4, v0
	v_mov_b32_e32 v5, v0
	v_mov_b32_e32 v6, v0
	v_mov_b32_e32 v7, v0
	v_mov_b32_e32 v16, v0
	v_mov_b32_e32 v17, v0
	v_mov_b32_e32 v18, v0
	v_mov_b32_e32 v19, v0
	v_mov_b32_e32 v20, v0
	v_mov_b32_e32 v21, v0
	v_mov_b32_e32 v22, v0
	v_mov_b32_e32 v23, v0
	v_mov_b32_e32 v32, v0
	v_mov_b32_e32 v33, v0
	v_mov_b32_e32 v34, v0
	v_mov_b32_e32 v35, v0
	v_mov_b32_e32 v36, v0
	v_mov_b32_e32 v37, v0
	v_mov_b32_e32 v38, v0
	v_mov_b32_e32 v39, v0
	v_mov_b32_e32 v48, v0
	v_mov_b32_e32 v49, v0
	v_mov_b32_e32 v50, v0
	v_mov_b32_e32 v51, v0
	v_mov_b32_e32 v52, v0
	v_mov_b32_e32 v53, v0
	v_mov_b32_e32 v54, v0
	v_mov_b32_e32 v55, v0
	v_mov_b32_e32 v8, v0
	v_mov_b32_e32 v9, v0
	v_mov_b32_e32 v10, v0
	v_mov_b32_e32 v11, v0
	v_mov_b32_e32 v12, v0
	v_mov_b32_e32 v13, v0
	v_mov_b32_e32 v14, v0
	v_mov_b32_e32 v15, v0
	v_mov_b32_e32 v24, v0
	v_mov_b32_e32 v25, v0
	v_mov_b32_e32 v26, v0
	v_mov_b32_e32 v27, v0
	v_mov_b32_e32 v28, v0
	v_mov_b32_e32 v29, v0
	v_mov_b32_e32 v30, v0
	v_mov_b32_e32 v31, v0
	v_mov_b32_e32 v40, v0
	v_mov_b32_e32 v41, v0
	v_mov_b32_e32 v42, v0
	v_mov_b32_e32 v43, v0
	v_mov_b32_e32 v44, v0
	v_mov_b32_e32 v45, v0
	v_mov_b32_e32 v46, v0
	v_mov_b32_e32 v47, v0
	v_mov_b32_e32 v56, v0
	v_mov_b32_e32 v57, v0
	v_mov_b32_e32 v58, v0
	v_mov_b32_e32 v59, v0
	v_mov_b32_e32 v60, v0
	v_mov_b32_e32 v61, v0
	v_mov_b32_e32 v62, v0
	v_mov_b32_e32 v63, v0
	v_mov_b32_e32 v64, v0
	v_mov_b32_e32 v65, v0
	v_mov_b32_e32 v66, v0
	v_mov_b32_e32 v67, v0
	v_mov_b32_e32 v68, v0
	v_mov_b32_e32 v69, v0
	v_mov_b32_e32 v70, v0
	v_mov_b32_e32 v71, v0
	v_mov_b32_e32 v80, v0
	v_mov_b32_e32 v81, v0
	v_mov_b32_e32 v82, v0
	v_mov_b32_e32 v83, v0
	v_mov_b32_e32 v84, v0
	v_mov_b32_e32 v85, v0
	v_mov_b32_e32 v86, v0
	v_mov_b32_e32 v87, v0
	v_mov_b32_e32 v96, v0
	v_mov_b32_e32 v97, v0
	v_mov_b32_e32 v98, v0
	v_mov_b32_e32 v99, v0
	v_mov_b32_e32 v100, v0
	v_mov_b32_e32 v101, v0
	v_mov_b32_e32 v102, v0
	v_mov_b32_e32 v103, v0
	v_mov_b32_e32 v112, v0
	v_mov_b32_e32 v113, v0
	v_mov_b32_e32 v114, v0
	v_mov_b32_e32 v115, v0
	v_mov_b32_e32 v116, v0
	v_mov_b32_e32 v117, v0
	v_mov_b32_e32 v118, v0
	v_mov_b32_e32 v119, v0
	v_mov_b32_e32 v72, v0
	v_mov_b32_e32 v73, v0
	v_mov_b32_e32 v74, v0
	v_mov_b32_e32 v75, v0
	v_mov_b32_e32 v76, v0
	v_mov_b32_e32 v77, v0
	v_mov_b32_e32 v78, v0
	v_mov_b32_e32 v79, v0
	v_mov_b32_e32 v88, v0
	v_mov_b32_e32 v89, v0
	v_mov_b32_e32 v90, v0
	v_mov_b32_e32 v91, v0
	v_mov_b32_e32 v92, v0
	v_mov_b32_e32 v93, v0
	v_mov_b32_e32 v94, v0
	v_mov_b32_e32 v95, v0
	v_mov_b32_e32 v104, v0
	v_mov_b32_e32 v105, v0
	v_mov_b32_e32 v106, v0
	v_mov_b32_e32 v107, v0
	v_mov_b32_e32 v108, v0
	v_mov_b32_e32 v109, v0
	v_mov_b32_e32 v110, v0
	v_mov_b32_e32 v111, v0
	v_mov_b32_e32 v120, v0
	v_mov_b32_e32 v121, v0
	v_mov_b32_e32 v122, v0
	v_mov_b32_e32 v123, v0
	v_mov_b32_e32 v124, v0
	v_mov_b32_e32 v125, v0
	v_mov_b32_e32 v126, v0
	v_mov_b32_e32 v127, v0
	v_add_u32_e32 v204, 0x80, v128
	v_add_u32_e32 v205, 0x80, v130
	v_add_u32_e32 v220, 0x80, v132
	v_add_u32_e32 v221, 0x80, v134
	.p2align	3

.LBB0_1192:
	s_ashr_i32 s17, s16, 31
	s_lshl_b64 s[18:19], s[16:17], 18
	s_add_u32 s18, s6, s18
	s_addc_u32 s19, s7, s19
	s_and_b64 s[20:21], s[4:5], exec
	s_cselect_b32 s17, s19, s27
	s_cselect_b32 s46, s18, s26
	s_ashr_i32 s15, s14, 31
	s_lshl_b64 s[20:21], s[14:15], 18
	s_add_u32 s20, s34, s20
	s_addc_u32 s21, s35, s21
	s_and_b64 s[28:29], s[4:5], exec
	s_cselect_b32 s15, s21, s25
	s_cselect_b32 s47, s20, s24
	s_add_u32 s48, s24, 0x100
	s_addc_u32 s49, s25, 0
	s_add_u32 s24, s26, 0x20080
	v_mov_b32_e32 v0, 0
	s_addc_u32 s25, s27, 0
	s_mov_b32 s50, -2
	v_mov_b32_e32 v1, v0
	v_mov_b32_e32 v2, v0
	v_mov_b32_e32 v3, v0
	v_mov_b32_e32 v4, v0
	v_mov_b32_e32 v5, v0
	v_mov_b32_e32 v6, v0
	v_mov_b32_e32 v7, v0
	v_mov_b32_e32 v16, v0
	v_mov_b32_e32 v17, v0
	v_mov_b32_e32 v18, v0
	v_mov_b32_e32 v19, v0
	v_mov_b32_e32 v20, v0
	v_mov_b32_e32 v21, v0
	v_mov_b32_e32 v22, v0
	v_mov_b32_e32 v23, v0
	v_mov_b32_e32 v32, v0
	v_mov_b32_e32 v33, v0
	v_mov_b32_e32 v34, v0
	v_mov_b32_e32 v35, v0
	v_mov_b32_e32 v36, v0
	v_mov_b32_e32 v37, v0
	v_mov_b32_e32 v38, v0
	v_mov_b32_e32 v39, v0
	v_mov_b32_e32 v48, v0
	v_mov_b32_e32 v49, v0
	v_mov_b32_e32 v50, v0
	v_mov_b32_e32 v51, v0
	v_mov_b32_e32 v52, v0
	v_mov_b32_e32 v53, v0
	v_mov_b32_e32 v54, v0
	v_mov_b32_e32 v55, v0
	v_mov_b32_e32 v8, v0
	v_mov_b32_e32 v9, v0
	v_mov_b32_e32 v10, v0
	v_mov_b32_e32 v11, v0
	v_mov_b32_e32 v12, v0
	v_mov_b32_e32 v13, v0
	v_mov_b32_e32 v14, v0
	v_mov_b32_e32 v15, v0
	v_mov_b32_e32 v24, v0
	v_mov_b32_e32 v25, v0
	v_mov_b32_e32 v26, v0
	v_mov_b32_e32 v27, v0
	v_mov_b32_e32 v28, v0
	v_mov_b32_e32 v29, v0
	v_mov_b32_e32 v30, v0
	v_mov_b32_e32 v31, v0
	v_mov_b32_e32 v40, v0
	v_mov_b32_e32 v41, v0
	v_mov_b32_e32 v42, v0
	v_mov_b32_e32 v43, v0
	v_mov_b32_e32 v44, v0
	v_mov_b32_e32 v45, v0
	v_mov_b32_e32 v46, v0
	v_mov_b32_e32 v47, v0
	v_mov_b32_e32 v56, v0
	v_mov_b32_e32 v57, v0
	v_mov_b32_e32 v58, v0
	v_mov_b32_e32 v59, v0
	v_mov_b32_e32 v60, v0
	v_mov_b32_e32 v61, v0
	v_mov_b32_e32 v62, v0
	v_mov_b32_e32 v63, v0
	v_mov_b32_e32 v64, v0
	v_mov_b32_e32 v65, v0
	v_mov_b32_e32 v66, v0
	v_mov_b32_e32 v67, v0
	v_mov_b32_e32 v68, v0
	v_mov_b32_e32 v69, v0
	v_mov_b32_e32 v70, v0
	v_mov_b32_e32 v71, v0
	v_mov_b32_e32 v80, v0
	v_mov_b32_e32 v81, v0
	v_mov_b32_e32 v82, v0
	v_mov_b32_e32 v83, v0
	v_mov_b32_e32 v84, v0
	v_mov_b32_e32 v85, v0
	v_mov_b32_e32 v86, v0
	v_mov_b32_e32 v87, v0
	v_mov_b32_e32 v96, v0
	v_mov_b32_e32 v97, v0
	v_mov_b32_e32 v98, v0
	v_mov_b32_e32 v99, v0
	v_mov_b32_e32 v100, v0
	v_mov_b32_e32 v101, v0
	v_mov_b32_e32 v102, v0
	v_mov_b32_e32 v103, v0
	v_mov_b32_e32 v112, v0
	v_mov_b32_e32 v113, v0
	v_mov_b32_e32 v114, v0
	v_mov_b32_e32 v115, v0
	v_mov_b32_e32 v116, v0
	v_mov_b32_e32 v117, v0
	v_mov_b32_e32 v118, v0
	v_mov_b32_e32 v119, v0
	v_mov_b32_e32 v72, v0
	v_mov_b32_e32 v73, v0
	v_mov_b32_e32 v74, v0
	v_mov_b32_e32 v75, v0
	v_mov_b32_e32 v76, v0
	v_mov_b32_e32 v77, v0
	v_mov_b32_e32 v78, v0
	v_mov_b32_e32 v79, v0
	v_mov_b32_e32 v88, v0
	v_mov_b32_e32 v89, v0
	v_mov_b32_e32 v90, v0
	v_mov_b32_e32 v91, v0
	v_mov_b32_e32 v92, v0
	v_mov_b32_e32 v93, v0
	v_mov_b32_e32 v94, v0
	v_mov_b32_e32 v95, v0
	v_mov_b32_e32 v104, v0
	v_mov_b32_e32 v105, v0
	v_mov_b32_e32 v106, v0
	v_mov_b32_e32 v107, v0
	v_mov_b32_e32 v108, v0
	v_mov_b32_e32 v109, v0
	v_mov_b32_e32 v110, v0
	v_mov_b32_e32 v111, v0
	v_mov_b32_e32 v120, v0
	v_mov_b32_e32 v121, v0
	v_mov_b32_e32 v122, v0
	v_mov_b32_e32 v123, v0
	v_mov_b32_e32 v124, v0
	v_mov_b32_e32 v125, v0
	v_mov_b32_e32 v126, v0
	v_mov_b32_e32 v127, v0
	v_add_u32_e32 v216, 0x80, v128
	v_add_u32_e32 v217, 0x80, v130
	v_add_u32_e32 v218, 0x80, v132
	v_add_u32_e32 v219, 0x80, v134
	.p2align	3

.LBB0_1364:
	s_ashr_i32 s19, s18, 31
	s_lshl_b64 s[20:21], s[18:19], 19
	s_add_u32 s20, s34, s20
	s_addc_u32 s21, s35, s21
	s_and_b64 s[22:23], s[4:5], exec
	s_cselect_b32 s19, s21, s27
	s_cselect_b32 s49, s20, s26
	s_ashr_i32 s17, s16, 31
	s_lshl_b64 s[22:23], s[16:17], 19
	s_add_u32 s22, s36, s22
	s_addc_u32 s23, s37, s23
	s_and_b64 s[28:29], s[4:5], exec
	s_cselect_b32 s17, s23, s25
	s_cselect_b32 s50, s22, s24
	s_add_u32 s51, s24, 0x100
	s_addc_u32 s52, s25, 0
	s_add_u32 s24, s26, 0x40080
	v_mov_b32_e32 v0, 0
	s_addc_u32 s25, s27, 0
	s_mov_b32 s53, -2
	v_mov_b32_e32 v1, v0
	v_mov_b32_e32 v2, v0
	v_mov_b32_e32 v3, v0
	v_mov_b32_e32 v4, v0
	v_mov_b32_e32 v5, v0
	v_mov_b32_e32 v6, v0
	v_mov_b32_e32 v7, v0
	v_mov_b32_e32 v16, v0
	v_mov_b32_e32 v17, v0
	v_mov_b32_e32 v18, v0
	v_mov_b32_e32 v19, v0
	v_mov_b32_e32 v20, v0
	v_mov_b32_e32 v21, v0
	v_mov_b32_e32 v22, v0
	v_mov_b32_e32 v23, v0
	v_mov_b32_e32 v32, v0
	v_mov_b32_e32 v33, v0
	v_mov_b32_e32 v34, v0
	v_mov_b32_e32 v35, v0
	v_mov_b32_e32 v36, v0
	v_mov_b32_e32 v37, v0
	v_mov_b32_e32 v38, v0
	v_mov_b32_e32 v39, v0
	v_mov_b32_e32 v48, v0
	v_mov_b32_e32 v49, v0
	v_mov_b32_e32 v50, v0
	v_mov_b32_e32 v51, v0
	v_mov_b32_e32 v52, v0
	v_mov_b32_e32 v53, v0
	v_mov_b32_e32 v54, v0
	v_mov_b32_e32 v55, v0
	v_mov_b32_e32 v8, v0
	v_mov_b32_e32 v9, v0
	v_mov_b32_e32 v10, v0
	v_mov_b32_e32 v11, v0
	v_mov_b32_e32 v12, v0
	v_mov_b32_e32 v13, v0
	v_mov_b32_e32 v14, v0
	v_mov_b32_e32 v15, v0
	v_mov_b32_e32 v24, v0
	v_mov_b32_e32 v25, v0
	v_mov_b32_e32 v26, v0
	v_mov_b32_e32 v27, v0
	v_mov_b32_e32 v28, v0
	v_mov_b32_e32 v29, v0
	v_mov_b32_e32 v30, v0
	v_mov_b32_e32 v31, v0
	v_mov_b32_e32 v40, v0
	v_mov_b32_e32 v41, v0
	v_mov_b32_e32 v42, v0
	v_mov_b32_e32 v43, v0
	v_mov_b32_e32 v44, v0
	v_mov_b32_e32 v45, v0
	v_mov_b32_e32 v46, v0
	v_mov_b32_e32 v47, v0
	v_mov_b32_e32 v56, v0
	v_mov_b32_e32 v57, v0
	v_mov_b32_e32 v58, v0
	v_mov_b32_e32 v59, v0
	v_mov_b32_e32 v60, v0
	v_mov_b32_e32 v61, v0
	v_mov_b32_e32 v62, v0
	v_mov_b32_e32 v63, v0
	v_mov_b32_e32 v64, v0
	v_mov_b32_e32 v65, v0
	v_mov_b32_e32 v66, v0
	v_mov_b32_e32 v67, v0
	v_mov_b32_e32 v68, v0
	v_mov_b32_e32 v69, v0
	v_mov_b32_e32 v70, v0
	v_mov_b32_e32 v71, v0
	v_mov_b32_e32 v80, v0
	v_mov_b32_e32 v81, v0
	v_mov_b32_e32 v82, v0
	v_mov_b32_e32 v83, v0
	v_mov_b32_e32 v84, v0
	v_mov_b32_e32 v85, v0
	v_mov_b32_e32 v86, v0
	v_mov_b32_e32 v87, v0
	v_mov_b32_e32 v96, v0
	v_mov_b32_e32 v97, v0
	v_mov_b32_e32 v98, v0
	v_mov_b32_e32 v99, v0
	v_mov_b32_e32 v100, v0
	v_mov_b32_e32 v101, v0
	v_mov_b32_e32 v102, v0
	v_mov_b32_e32 v103, v0
	v_mov_b32_e32 v112, v0
	v_mov_b32_e32 v113, v0
	v_mov_b32_e32 v114, v0
	v_mov_b32_e32 v115, v0
	v_mov_b32_e32 v116, v0
	v_mov_b32_e32 v117, v0
	v_mov_b32_e32 v118, v0
	v_mov_b32_e32 v119, v0
	v_mov_b32_e32 v72, v0
	v_mov_b32_e32 v73, v0
	v_mov_b32_e32 v74, v0
	v_mov_b32_e32 v75, v0
	v_mov_b32_e32 v76, v0
	v_mov_b32_e32 v77, v0
	v_mov_b32_e32 v78, v0
	v_mov_b32_e32 v79, v0
	v_mov_b32_e32 v88, v0
	v_mov_b32_e32 v89, v0
	v_mov_b32_e32 v90, v0
	v_mov_b32_e32 v91, v0
	v_mov_b32_e32 v92, v0
	v_mov_b32_e32 v93, v0
	v_mov_b32_e32 v94, v0
	v_mov_b32_e32 v95, v0
	v_mov_b32_e32 v104, v0
	v_mov_b32_e32 v105, v0
	v_mov_b32_e32 v106, v0
	v_mov_b32_e32 v107, v0
	v_mov_b32_e32 v108, v0
	v_mov_b32_e32 v109, v0
	v_mov_b32_e32 v110, v0
	v_mov_b32_e32 v111, v0
	v_mov_b32_e32 v120, v0
	v_mov_b32_e32 v121, v0
	v_mov_b32_e32 v122, v0
	v_mov_b32_e32 v123, v0
	v_mov_b32_e32 v124, v0
	v_mov_b32_e32 v125, v0
	v_mov_b32_e32 v126, v0
	v_mov_b32_e32 v127, v0
	v_add_u32_e32 v204, 0x80, v128
	v_add_u32_e32 v205, 0x80, v130
	v_add_u32_e32 v220, 0x80, v132
	v_add_u32_e32 v221, 0x80, v134
	.p2align	3

.LBB0_1560:
	s_ashr_i32 s29, s28, 31
	s_lshl_b64 s[30:31], s[28:29], 19
	s_add_u32 s30, s12, s30
	s_addc_u32 s31, s13, s31
	s_and_b64 s[34:35], s[6:7], exec
	s_cselect_b32 s3, s31, s39
	s_cselect_b32 s29, s30, s38
	s_ashr_i32 s27, s26, 31
	s_lshl_b64 s[34:35], s[26:27], 19
	s_add_u32 s34, s43, s34
	s_addc_u32 s35, s44, s35
	s_and_b64 s[40:41], s[6:7], exec
	s_cselect_b32 s27, s35, s37
	s_cselect_b32 s58, s34, s36
	s_add_u32 s59, s36, 0x100
	s_addc_u32 s60, s37, 0
	s_add_u32 s36, s38, 0x40080
	v_mov_b32_e32 v0, 0
	s_addc_u32 s37, s39, 0
	s_mov_b32 s61, -2
	v_mov_b32_e32 v1, v0
	v_mov_b32_e32 v2, v0
	v_mov_b32_e32 v3, v0
	v_mov_b32_e32 v4, v0
	v_mov_b32_e32 v5, v0
	v_mov_b32_e32 v6, v0
	v_mov_b32_e32 v7, v0
	v_mov_b32_e32 v16, v0
	v_mov_b32_e32 v17, v0
	v_mov_b32_e32 v18, v0
	v_mov_b32_e32 v19, v0
	v_mov_b32_e32 v20, v0
	v_mov_b32_e32 v21, v0
	v_mov_b32_e32 v22, v0
	v_mov_b32_e32 v23, v0
	v_mov_b32_e32 v32, v0
	v_mov_b32_e32 v33, v0
	v_mov_b32_e32 v34, v0
	v_mov_b32_e32 v35, v0
	v_mov_b32_e32 v36, v0
	v_mov_b32_e32 v37, v0
	v_mov_b32_e32 v38, v0
	v_mov_b32_e32 v39, v0
	v_mov_b32_e32 v48, v0
	v_mov_b32_e32 v49, v0
	v_mov_b32_e32 v50, v0
	v_mov_b32_e32 v51, v0
	v_mov_b32_e32 v52, v0
	v_mov_b32_e32 v53, v0
	v_mov_b32_e32 v54, v0
	v_mov_b32_e32 v55, v0
	v_mov_b32_e32 v8, v0
	v_mov_b32_e32 v9, v0
	v_mov_b32_e32 v10, v0
	v_mov_b32_e32 v11, v0
	v_mov_b32_e32 v12, v0
	v_mov_b32_e32 v13, v0
	v_mov_b32_e32 v14, v0
	v_mov_b32_e32 v15, v0
	v_mov_b32_e32 v24, v0
	v_mov_b32_e32 v25, v0
	v_mov_b32_e32 v26, v0
	v_mov_b32_e32 v27, v0
	v_mov_b32_e32 v28, v0
	v_mov_b32_e32 v29, v0
	v_mov_b32_e32 v30, v0
	v_mov_b32_e32 v31, v0
	v_mov_b32_e32 v40, v0
	v_mov_b32_e32 v41, v0
	v_mov_b32_e32 v42, v0
	v_mov_b32_e32 v43, v0
	v_mov_b32_e32 v44, v0
	v_mov_b32_e32 v45, v0
	v_mov_b32_e32 v46, v0
	v_mov_b32_e32 v47, v0
	v_mov_b32_e32 v56, v0
	v_mov_b32_e32 v57, v0
	v_mov_b32_e32 v58, v0
	v_mov_b32_e32 v59, v0
	v_mov_b32_e32 v60, v0
	v_mov_b32_e32 v61, v0
	v_mov_b32_e32 v62, v0
	v_mov_b32_e32 v63, v0
	v_mov_b32_e32 v64, v0
	v_mov_b32_e32 v65, v0
	v_mov_b32_e32 v66, v0
	v_mov_b32_e32 v67, v0
	v_mov_b32_e32 v68, v0
	v_mov_b32_e32 v69, v0
	v_mov_b32_e32 v70, v0
	v_mov_b32_e32 v71, v0
	v_mov_b32_e32 v80, v0
	v_mov_b32_e32 v81, v0
	v_mov_b32_e32 v82, v0
	v_mov_b32_e32 v83, v0
	v_mov_b32_e32 v84, v0
	v_mov_b32_e32 v85, v0
	v_mov_b32_e32 v86, v0
	v_mov_b32_e32 v87, v0
	v_mov_b32_e32 v96, v0
	v_mov_b32_e32 v97, v0
	v_mov_b32_e32 v98, v0
	v_mov_b32_e32 v99, v0
	v_mov_b32_e32 v100, v0
	v_mov_b32_e32 v101, v0
	v_mov_b32_e32 v102, v0
	v_mov_b32_e32 v103, v0
	v_mov_b32_e32 v112, v0
	v_mov_b32_e32 v113, v0
	v_mov_b32_e32 v114, v0
	v_mov_b32_e32 v115, v0
	v_mov_b32_e32 v116, v0
	v_mov_b32_e32 v117, v0
	v_mov_b32_e32 v118, v0
	v_mov_b32_e32 v119, v0
	v_mov_b32_e32 v72, v0
	v_mov_b32_e32 v73, v0
	v_mov_b32_e32 v74, v0
	v_mov_b32_e32 v75, v0
	v_mov_b32_e32 v76, v0
	v_mov_b32_e32 v77, v0
	v_mov_b32_e32 v78, v0
	v_mov_b32_e32 v79, v0
	v_mov_b32_e32 v88, v0
	v_mov_b32_e32 v89, v0
	v_mov_b32_e32 v90, v0
	v_mov_b32_e32 v91, v0
	v_mov_b32_e32 v92, v0
	v_mov_b32_e32 v93, v0
	v_mov_b32_e32 v94, v0
	v_mov_b32_e32 v95, v0
	v_mov_b32_e32 v104, v0
	v_mov_b32_e32 v105, v0
	v_mov_b32_e32 v106, v0
	v_mov_b32_e32 v107, v0
	v_mov_b32_e32 v108, v0
	v_mov_b32_e32 v109, v0
	v_mov_b32_e32 v110, v0
	v_mov_b32_e32 v111, v0
	v_mov_b32_e32 v120, v0
	v_mov_b32_e32 v121, v0
	v_mov_b32_e32 v122, v0
	v_mov_b32_e32 v123, v0
	v_mov_b32_e32 v124, v0
	v_mov_b32_e32 v125, v0
	v_mov_b32_e32 v126, v0
	v_mov_b32_e32 v127, v0
	v_add_u32_e32 v204, 0x80, v128
	v_add_u32_e32 v205, 0x80, v130
	.p2align	3

.LBB0_1645:
	s_ashr_i32 s19, s18, 31
	s_lshl_b64 s[20:21], s[18:19], 19
	s_add_u32 s20, s8, s20
	s_addc_u32 s21, s9, s21
	s_and_b64 s[22:23], s[4:5], exec
	s_cselect_b32 s19, s21, s27
	s_cselect_b32 s50, s20, s26
	s_ashr_i32 s17, s16, 31
	s_lshl_b64 s[22:23], s[16:17], 19
	s_add_u32 s22, s31, s22
	s_addc_u32 s23, s34, s23
	s_and_b64 s[28:29], s[4:5], exec
	s_cselect_b32 s17, s23, s25
	s_cselect_b32 s51, s22, s24
	s_add_u32 s52, s24, 0x100
	s_addc_u32 s53, s25, 0
	s_add_u32 s24, s26, 0x40080
	v_mov_b32_e32 v0, 0
	s_addc_u32 s25, s27, 0
	s_mov_b32 s54, -2
	v_mov_b32_e32 v1, v0
	v_mov_b32_e32 v2, v0
	v_mov_b32_e32 v3, v0
	v_mov_b32_e32 v4, v0
	v_mov_b32_e32 v5, v0
	v_mov_b32_e32 v6, v0
	v_mov_b32_e32 v7, v0
	v_mov_b32_e32 v16, v0
	v_mov_b32_e32 v17, v0
	v_mov_b32_e32 v18, v0
	v_mov_b32_e32 v19, v0
	v_mov_b32_e32 v20, v0
	v_mov_b32_e32 v21, v0
	v_mov_b32_e32 v22, v0
	v_mov_b32_e32 v23, v0
	v_mov_b32_e32 v32, v0
	v_mov_b32_e32 v33, v0
	v_mov_b32_e32 v34, v0
	v_mov_b32_e32 v35, v0
	v_mov_b32_e32 v36, v0
	v_mov_b32_e32 v37, v0
	v_mov_b32_e32 v38, v0
	v_mov_b32_e32 v39, v0
	v_mov_b32_e32 v48, v0
	v_mov_b32_e32 v49, v0
	v_mov_b32_e32 v50, v0
	v_mov_b32_e32 v51, v0
	v_mov_b32_e32 v52, v0
	v_mov_b32_e32 v53, v0
	v_mov_b32_e32 v54, v0
	v_mov_b32_e32 v55, v0
	v_mov_b32_e32 v8, v0
	v_mov_b32_e32 v9, v0
	v_mov_b32_e32 v10, v0
	v_mov_b32_e32 v11, v0
	v_mov_b32_e32 v12, v0
	v_mov_b32_e32 v13, v0
	v_mov_b32_e32 v14, v0
	v_mov_b32_e32 v15, v0
	v_mov_b32_e32 v24, v0
	v_mov_b32_e32 v25, v0
	v_mov_b32_e32 v26, v0
	v_mov_b32_e32 v27, v0
	v_mov_b32_e32 v28, v0
	v_mov_b32_e32 v29, v0
	v_mov_b32_e32 v30, v0
	v_mov_b32_e32 v31, v0
	v_mov_b32_e32 v40, v0
	v_mov_b32_e32 v41, v0
	v_mov_b32_e32 v42, v0
	v_mov_b32_e32 v43, v0
	v_mov_b32_e32 v44, v0
	v_mov_b32_e32 v45, v0
	v_mov_b32_e32 v46, v0
	v_mov_b32_e32 v47, v0
	v_mov_b32_e32 v56, v0
	v_mov_b32_e32 v57, v0
	v_mov_b32_e32 v58, v0
	v_mov_b32_e32 v59, v0
	v_mov_b32_e32 v60, v0
	v_mov_b32_e32 v61, v0
	v_mov_b32_e32 v62, v0
	v_mov_b32_e32 v63, v0
	v_mov_b32_e32 v64, v0
	v_mov_b32_e32 v65, v0
	v_mov_b32_e32 v66, v0
	v_mov_b32_e32 v67, v0
	v_mov_b32_e32 v68, v0
	v_mov_b32_e32 v69, v0
	v_mov_b32_e32 v70, v0
	v_mov_b32_e32 v71, v0
	v_mov_b32_e32 v80, v0
	v_mov_b32_e32 v81, v0
	v_mov_b32_e32 v82, v0
	v_mov_b32_e32 v83, v0
	v_mov_b32_e32 v84, v0
	v_mov_b32_e32 v85, v0
	v_mov_b32_e32 v86, v0
	v_mov_b32_e32 v87, v0
	v_mov_b32_e32 v96, v0
	v_mov_b32_e32 v97, v0
	v_mov_b32_e32 v98, v0
	v_mov_b32_e32 v99, v0
	v_mov_b32_e32 v100, v0
	v_mov_b32_e32 v101, v0
	v_mov_b32_e32 v102, v0
	v_mov_b32_e32 v103, v0
	v_mov_b32_e32 v112, v0
	v_mov_b32_e32 v113, v0
	v_mov_b32_e32 v114, v0
	v_mov_b32_e32 v115, v0
	v_mov_b32_e32 v116, v0
	v_mov_b32_e32 v117, v0
	v_mov_b32_e32 v118, v0
	v_mov_b32_e32 v119, v0
	v_mov_b32_e32 v72, v0
	v_mov_b32_e32 v73, v0
	v_mov_b32_e32 v74, v0
	v_mov_b32_e32 v75, v0
	v_mov_b32_e32 v76, v0
	v_mov_b32_e32 v77, v0
	v_mov_b32_e32 v78, v0
	v_mov_b32_e32 v79, v0
	v_mov_b32_e32 v88, v0
	v_mov_b32_e32 v89, v0
	v_mov_b32_e32 v90, v0
	v_mov_b32_e32 v91, v0
	v_mov_b32_e32 v92, v0
	v_mov_b32_e32 v93, v0
	v_mov_b32_e32 v94, v0
	v_mov_b32_e32 v95, v0
	v_mov_b32_e32 v104, v0
	v_mov_b32_e32 v105, v0
	v_mov_b32_e32 v106, v0
	v_mov_b32_e32 v107, v0
	v_mov_b32_e32 v108, v0
	v_mov_b32_e32 v109, v0
	v_mov_b32_e32 v110, v0
	v_mov_b32_e32 v111, v0
	v_mov_b32_e32 v120, v0
	v_mov_b32_e32 v121, v0
	v_mov_b32_e32 v122, v0
	v_mov_b32_e32 v123, v0
	v_mov_b32_e32 v124, v0
	v_mov_b32_e32 v125, v0
	v_mov_b32_e32 v126, v0
	v_mov_b32_e32 v127, v0
	v_add_u32_e32 v204, 0x80, v128
	v_add_u32_e32 v205, 0x80, v130
	v_add_u32_e32 v220, 0x80, v132
	v_add_u32_e32 v221, 0x80, v134
	.p2align	3

.LBB0_3040:
	s_ashr_i32 s29, s28, 31
	s_lshl_b64 s[30:31], s[28:29], 19
	s_add_u32 s30, s8, s30
	s_addc_u32 s31, s9, s31
	s_and_b64 s[34:35], s[6:7], exec
	s_cselect_b32 s3, s31, s39
	s_cselect_b32 s29, s30, s38
	s_ashr_i32 s27, s26, 31
	s_lshl_b64 s[34:35], s[26:27], 19
	s_add_u32 s34, s43, s34
	s_addc_u32 s35, s44, s35
	s_and_b64 s[40:41], s[6:7], exec
	s_cselect_b32 s27, s35, s37
	s_cselect_b32 s58, s34, s36
	s_add_u32 s59, s36, 0x100
	s_addc_u32 s60, s37, 0
	s_add_u32 s36, s38, 0x40080
	v_mov_b32_e32 v0, 0
	s_addc_u32 s37, s39, 0
	s_mov_b32 s61, -2
	v_mov_b32_e32 v1, v0
	v_mov_b32_e32 v2, v0
	v_mov_b32_e32 v3, v0
	v_mov_b32_e32 v4, v0
	v_mov_b32_e32 v5, v0
	v_mov_b32_e32 v6, v0
	v_mov_b32_e32 v7, v0
	v_mov_b32_e32 v16, v0
	v_mov_b32_e32 v17, v0
	v_mov_b32_e32 v18, v0
	v_mov_b32_e32 v19, v0
	v_mov_b32_e32 v20, v0
	v_mov_b32_e32 v21, v0
	v_mov_b32_e32 v22, v0
	v_mov_b32_e32 v23, v0
	v_mov_b32_e32 v32, v0
	v_mov_b32_e32 v33, v0
	v_mov_b32_e32 v34, v0
	v_mov_b32_e32 v35, v0
	v_mov_b32_e32 v36, v0
	v_mov_b32_e32 v37, v0
	v_mov_b32_e32 v38, v0
	v_mov_b32_e32 v39, v0
	v_mov_b32_e32 v48, v0
	v_mov_b32_e32 v49, v0
	v_mov_b32_e32 v50, v0
	v_mov_b32_e32 v51, v0
	v_mov_b32_e32 v52, v0
	v_mov_b32_e32 v53, v0
	v_mov_b32_e32 v54, v0
	v_mov_b32_e32 v55, v0
	v_mov_b32_e32 v8, v0
	v_mov_b32_e32 v9, v0
	v_mov_b32_e32 v10, v0
	v_mov_b32_e32 v11, v0
	v_mov_b32_e32 v12, v0
	v_mov_b32_e32 v13, v0
	v_mov_b32_e32 v14, v0
	v_mov_b32_e32 v15, v0
	v_mov_b32_e32 v24, v0
	v_mov_b32_e32 v25, v0
	v_mov_b32_e32 v26, v0
	v_mov_b32_e32 v27, v0
	v_mov_b32_e32 v28, v0
	v_mov_b32_e32 v29, v0
	v_mov_b32_e32 v30, v0
	v_mov_b32_e32 v31, v0
	v_mov_b32_e32 v40, v0
	v_mov_b32_e32 v41, v0
	v_mov_b32_e32 v42, v0
	v_mov_b32_e32 v43, v0
	v_mov_b32_e32 v44, v0
	v_mov_b32_e32 v45, v0
	v_mov_b32_e32 v46, v0
	v_mov_b32_e32 v47, v0
	v_mov_b32_e32 v56, v0
	v_mov_b32_e32 v57, v0
	v_mov_b32_e32 v58, v0
	v_mov_b32_e32 v59, v0
	v_mov_b32_e32 v60, v0
	v_mov_b32_e32 v61, v0
	v_mov_b32_e32 v62, v0
	v_mov_b32_e32 v63, v0
	v_mov_b32_e32 v64, v0
	v_mov_b32_e32 v65, v0
	v_mov_b32_e32 v66, v0
	v_mov_b32_e32 v67, v0
	v_mov_b32_e32 v68, v0
	v_mov_b32_e32 v69, v0
	v_mov_b32_e32 v70, v0
	v_mov_b32_e32 v71, v0
	v_mov_b32_e32 v80, v0
	v_mov_b32_e32 v81, v0
	v_mov_b32_e32 v82, v0
	v_mov_b32_e32 v83, v0
	v_mov_b32_e32 v84, v0
	v_mov_b32_e32 v85, v0
	v_mov_b32_e32 v86, v0
	v_mov_b32_e32 v87, v0
	v_mov_b32_e32 v96, v0
	v_mov_b32_e32 v97, v0
	v_mov_b32_e32 v98, v0
	v_mov_b32_e32 v99, v0
	v_mov_b32_e32 v100, v0
	v_mov_b32_e32 v101, v0
	v_mov_b32_e32 v102, v0
	v_mov_b32_e32 v103, v0
	v_mov_b32_e32 v112, v0
	v_mov_b32_e32 v113, v0
	v_mov_b32_e32 v114, v0
	v_mov_b32_e32 v115, v0
	v_mov_b32_e32 v116, v0
	v_mov_b32_e32 v117, v0
	v_mov_b32_e32 v118, v0
	v_mov_b32_e32 v119, v0
	v_mov_b32_e32 v72, v0
	v_mov_b32_e32 v73, v0
	v_mov_b32_e32 v74, v0
	v_mov_b32_e32 v75, v0
	v_mov_b32_e32 v76, v0
	v_mov_b32_e32 v77, v0
	v_mov_b32_e32 v78, v0
	v_mov_b32_e32 v79, v0
	v_mov_b32_e32 v88, v0
	v_mov_b32_e32 v89, v0
	v_mov_b32_e32 v90, v0
	v_mov_b32_e32 v91, v0
	v_mov_b32_e32 v92, v0
	v_mov_b32_e32 v93, v0
	v_mov_b32_e32 v94, v0
	v_mov_b32_e32 v95, v0
	v_mov_b32_e32 v104, v0
	v_mov_b32_e32 v105, v0
	v_mov_b32_e32 v106, v0
	v_mov_b32_e32 v107, v0
	v_mov_b32_e32 v108, v0
	v_mov_b32_e32 v109, v0
	v_mov_b32_e32 v110, v0
	v_mov_b32_e32 v111, v0
	v_mov_b32_e32 v120, v0
	v_mov_b32_e32 v121, v0
	v_mov_b32_e32 v122, v0
	v_mov_b32_e32 v123, v0
	v_mov_b32_e32 v124, v0
	v_mov_b32_e32 v125, v0
	v_mov_b32_e32 v126, v0
	v_mov_b32_e32 v127, v0
	v_add_u32_e32 v204, 0x80, v128
	v_add_u32_e32 v205, 0x80, v130
	.p2align	3
